# speedup vs baseline: 1.0066x; 1.0030x over previous
; DI int tid_() { int t = threadIdx.x; asm volatile("" : "+v"(t)); return t; }
; DI int bid_() { int b = blockIdx.x; asm volatile("" : "+s"(b)); return b; }
; DI void phase_hg2(const Params& p, int L) {
;     ...
;   for (int idx = bid_() * 512 + tid_(); idx < ncombo * 16384; idx += gridDim.x * 512) {
;     const int combo = idx >> 14, e = idx & 16383, k = e >> 7; const int dir = (combo >> 3) & 1;
;     const long s_st = dir ? -16384 : 16384; const int s_pv = dir ? -128 : 128;
;     float* sp = ST + ((size_t)combo * nsc + (dir ? nsc - 1 : 0)) * 16384 + e;
;     const float* pp = PV + ((size_t)combo * nsc + (dir ? nsc - 1 : 0)) * 128 + k;
;     float carry = 0.f;
;     for (int j0 = 0; j0 < nsc; j0 += 8) {
;       float tmp[8], pv[8];
; #pragma unroll
;       for (int u = 0; u < 8; ++u) { tmp[u] = sp[u * s_st]; pv[u] = pp[u * s_pv]; }
; #pragma unroll
;       for (int u = 0; u < 8; ++u) { sp[u * s_st] = carry; carry = pv[u] * carry + tmp[u]; }
;       sp += 8 * s_st; pp += 8 * s_pv;
;     }
;   }
.LBB0_90:
	v_lshl_add_u64 v[28:29], s[26:27], 0, v[2:3]
	v_lshl_add_u64 v[30:31], s[26:27], 0, v[6:7]
	global_load_dword v27, v[30:31], off nt
	global_load_dword v46, v[28:29], off
	v_lshl_add_u64 v[32:33], s[26:27], 0, v[22:23]
	v_lshl_add_u64 v[28:29], v[28:29], 0, v[0:1]
	global_load_dword v47, v[32:33], off nt
	global_load_dword v48, v[28:29], off
	v_lshl_add_u64 v[34:35], s[26:27], 0, v[10:11]
	v_lshl_add_u64 v[28:29], v[28:29], 0, v[0:1]
	global_load_dword v49, v[34:35], off nt
	global_load_dword v50, v[28:29], off
	v_lshl_add_u64 v[36:37], s[26:27], 0, v[12:13]
	v_lshl_add_u64 v[28:29], v[28:29], 0, v[0:1]
	global_load_dword v51, v[36:37], off nt
	global_load_dword v52, v[28:29], off
	v_lshl_add_u64 v[38:39], s[26:27], 0, v[14:15]
	v_lshl_add_u64 v[28:29], v[28:29], 0, v[0:1]
	global_load_dword v53, v[38:39], off nt
	global_load_dword v54, v[28:29], off
	v_lshl_add_u64 v[40:41], s[26:27], 0, v[16:17]
	v_lshl_add_u64 v[28:29], v[28:29], 0, v[0:1]
	global_load_dword v55, v[40:41], off nt
	global_load_dword v56, v[28:29], off
	v_lshl_add_u64 v[42:43], s[26:27], 0, v[18:19]
	v_lshl_add_u64 v[28:29], v[28:29], 0, v[0:1]
	global_load_dword v57, v[42:43], off nt
	global_load_dword v58, v[28:29], off
	v_lshl_add_u64 v[44:45], s[26:27], 0, v[20:21]
	v_lshl_add_u64 v[28:29], v[28:29], 0, v[0:1]
	global_load_dword v59, v[44:45], off nt
	s_add_i32 s40, s40, 8
	global_load_dword v28, v[28:29], off
	v_lshl_add_u64 v[2:3], v[2:3], 0, v[4:5]
	global_store_dword v[30:31], v26, off
	v_lshl_add_u64 v[6:7], v[6:7], 0, v[8:9]
	v_lshl_add_u64 v[10:11], v[10:11], 0, v[8:9]
	v_lshl_add_u64 v[12:13], v[12:13], 0, v[8:9]
	v_lshl_add_u64 v[14:15], v[14:15], 0, v[8:9]
	v_lshl_add_u64 v[16:17], v[16:17], 0, v[8:9]
	v_lshl_add_u64 v[18:19], v[18:19], 0, v[8:9]
	v_lshl_add_u64 v[20:21], v[20:21], 0, v[8:9]
	v_lshl_add_u64 v[22:23], v[22:23], 0, v[8:9]
	s_cmp_lt_u32 s40, s7
	s_waitcnt vmcnt(15)
	v_fmac_f32_e32 v27, v26, v46
	global_store_dword v[32:33], v27, off
	s_waitcnt vmcnt(14)
	v_fmac_f32_e32 v47, v27, v48
	global_store_dword v[34:35], v47, off
	s_waitcnt vmcnt(13)
	v_fmac_f32_e32 v49, v47, v50
	global_store_dword v[36:37], v49, off
	s_waitcnt vmcnt(12)
	v_fmac_f32_e32 v51, v49, v52
	global_store_dword v[38:39], v51, off
	s_waitcnt vmcnt(11)
	v_fmac_f32_e32 v53, v51, v54
	global_store_dword v[40:41], v53, off
	s_waitcnt vmcnt(10)
	v_fmac_f32_e32 v55, v53, v56
	global_store_dword v[42:43], v55, off
	s_waitcnt vmcnt(9)
	v_fmac_f32_e32 v57, v55, v58
	global_store_dword v[44:45], v57, off
	s_waitcnt vmcnt(8)
	v_fmac_f32_e32 v59, v57, v28
	v_mov_b32_e32 v26, v59
	s_cbranch_scc1 .LBB0_90
	v_add_u32_e32 v24, s58, v24
	v_cmp_le_i32_e32 vcc, s6, v24
	s_or_b64 s[38:39], vcc, s[38:39]
	v_add_u16_e32 v25, s58, v25
	s_andn2_b64 exec, exec, s[38:39]
	s_cbranch_execnz .LBB0_89
